# LRU pass item ranges rebalanced: 128 blocks x 9 items + 384 x 8 (was 470 x 9 with 42 idle blocks)
# speedup vs baseline: 1.1723x; 1.0029x over previous
.LBB0_933:
	s_or_b64 exec, exec, s[0:1]
	s_add_u32 s42, s52, 0xb983000
	s_mul_i32 s1, s12, s8
	s_addc_u32 s43, s53, 0
	s_sub_i32 s1, s10, s1
	s_xor_b32 s0, s9, s11
	s_add_i32 s2, s12, 1
	s_sub_i32 s3, s1, s8
	s_cmp_ge_u32 s1, s8
	s_cselect_b32 s2, s2, s12
	s_cselect_b32 s1, s3, s1
	s_add_i32 s3, s2, 1
	s_cmp_ge_u32 s1, s8
	s_cselect_b32 s1, s3, s2
	s_xor_b32 s1, s1, s0
	s_sub_i32 s0, s1, s0
	v_readlane_b32 s1, v254, 56
	s_mul_i32 s78, s0, s1
	s_add_i32 s0, s78, s0
	s_sub_i32 s68, s0, s78
	s_cmp_eq_u32 s68, 9
	s_cbranch_scc0 .Lbal_skip
	s_cmpk_lt_i32 s1, 0x80
	s_cbranch_scc1 .Lbal_skip
	s_lshl_b32 s78, s1, 3
	s_addk_i32 s78, 0x80
	s_add_i32 s0, s78, 8
.Lbal_skip:
	s_add_u32 s54, s52, 0xb818000
	s_addc_u32 s55, s53, 0
	s_min_i32 s79, s0, 0x1080
	s_cmp_lt_i32 s78, s79
	s_cselect_b64 s[62:63], -1, 0
	s_cmp_ge_i32 s78, s79
	s_cbranch_scc1 .LBB0_996
	s_mov_b32 s10, 0x2e8ba2e9
	v_mul_hi_i32 v1, v0, s10
	v_ashrrev_i32_e32 v2, 1, v1
	v_lshrrev_b32_e32 v3, 31, v1
	v_add_u32_e32 v138, v2, v3
	v_ashrrev_i32_e32 v1, 2, v1
	v_mul_lo_u32 v2, v138, 11
	v_add_u32_e32 v1, v1, v3
	v_ashrrev_i32_e32 v4, 7, v0
	v_sub_u32_e32 v5, v0, v2
	v_mul_lo_u32 v2, v1, 22
	s_movk_i32 s4, 0x6400
	v_sub_u32_e32 v6, v0, v2
	v_lshlrev_b32_e32 v176, 4, v4
	v_and_b32_e32 v2, 48, v0
	v_mul_lo_u32 v4, v4, s4
	v_lshlrev_b32_e32 v144, 4, v6
	v_or_b32_e32 v13, v2, v4
	v_lshlrev_b32_e32 v4, 3, v6
	v_lshlrev_b32_e32 v177, 5, v5
	v_lshlrev_b32_e32 v178, 4, v5
	v_sub_u32_e32 v14, v144, v4
	v_mad_u64_u32 v[4:5], s[6:7], v138, -11, v[0:1]
	v_add_u32_e32 v6, 0x100, v0
	v_mul_hi_i32 v5, v6, s10
	v_lshrrev_b32_e32 v7, 31, v5
	v_ashrrev_i32_e32 v5, 1, v5
	v_add_u32_e32 v148, v5, v7
	v_add_u32_e32 v8, 0x200, v0
	v_mov_b32_e32 v141, 0
	v_mad_u64_u32 v[6:7], s[8:9], v148, -11, v[6:7]
	v_mul_hi_i32 v5, v8, s10
	v_mov_b32_e32 v3, v141
	v_lshrrev_b32_e32 v7, 31, v5
	v_ashrrev_i32_e32 v5, 1, v5
	v_and_b32_e32 v10, 15, v0
	v_lshlrev_b32_e32 v11, 2, v0
	v_lshl_add_u64 v[142:143], s[90:91], 0, v[2:3]
	v_lshrrev_b32_e32 v3, 1, v0
	v_add_u32_e32 v152, v5, v7
	v_add_u32_e32 v145, 0x12a20, v11
	v_and_or_b32 v3, v3, 32, v10
	v_mad_u64_u32 v[8:9], s[10:11], v152, -11, v[8:9]
	v_mul_u32_u24_e32 v10, 0x60, v10
	s_movk_i32 s18, 0xb0
	s_movk_i32 s22, 0xd0
	s_movk_i32 s20, 0x190
	v_mov_b32_e32 v56, v141
	v_mov_b32_e32 v57, v141
	s_movk_i32 s0, 0x58
	s_movk_i32 s2, 0xfd
	s_movk_i32 s4, 0xf2
	v_lshlrev_b32_e32 v146, 3, v4
	s_movk_i32 s8, 0xff20
	v_lshlrev_b32_e32 v150, 3, v6
	s_movk_i32 s10, 0xfe20
	v_lshlrev_b32_e32 v154, 3, v8
	v_or_b32_e32 v12, 0x1800, v10
	s_movk_i32 s12, 0x2e1
	v_mul_lo_u32 v179, v138, s18
	v_lshlrev_b32_e32 v7, 4, v4
	s_movk_i32 s14, 0x1e1
	v_mul_lo_u32 v9, v148, s18
	v_lshlrev_b32_e32 v6, 4, v6
	s_movk_i32 s16, 0xe1
	v_mul_lo_u32 v15, v152, s18
	v_lshlrev_b32_e32 v8, 4, v8
	v_mul_lo_u32 v16, v138, s22
	s_movk_i32 s18, 0xc6
	v_mul_u32_u24_e32 v17, 0xd0, v3
	v_mul_u32_u24_e32 v3, 0x190, v3
	v_mad_u64_u32 v[156:157], s[20:21], v1, s20, v[144:145]
	v_mul_lo_u32 v18, v1, s22
	v_add_u32_e32 v189, 0x6220, v11
	v_mov_b32_e32 v4, v141
	v_mov_b32_e32 v5, v141
	v_mov_b32_e32 v54, v141
	v_mov_b32_e32 v55, v141
	v_mov_b64_e32 v[100:101], v[56:57]
	v_mov_b64_e32 v[96:97], v[56:57]
	v_mov_b64_e32 v[88:89], v[56:57]
	v_mov_b64_e32 v[80:81], v[56:57]
	v_mov_b64_e32 v[76:77], v[56:57]
	v_mov_b64_e32 v[116:117], v[56:57]
	v_mov_b64_e32 v[72:73], v[56:57]
	v_mov_b64_e32 v[108:109], v[56:57]
	v_mov_b64_e32 v[64:65], v[56:57]
	v_mov_b64_e32 v[104:105], v[56:57]
	v_mov_b64_e32 v[60:61], v[56:57]
	v_mov_b64_e32 v[124:125], v[56:57]
	v_mov_b64_e32 v[92:93], v[56:57]
	v_mov_b64_e32 v[120:121], v[56:57]
	v_mov_b64_e32 v[84:85], v[56:57]
	v_mov_b64_e32 v[112:113], v[56:57]
	v_mov_b64_e32 v[68:69], v[56:57]
	v_cmp_gt_i32_e64 s[0:1], s0, v0
	s_mov_b64 s[56:57], s[90:91]
	v_cmp_gt_i32_e64 s[2:3], s2, v0
	v_cmp_gt_i32_e64 s[72:73], s4, v0
	v_cmp_lt_i32_e64 s[74:75], 32, v0
	v_ashrrev_i32_e32 v139, 31, v138
	v_ashrrev_i32_e32 v147, 31, v146
	v_cmp_lt_i32_e64 s[76:77], s8, v0
	v_ashrrev_i32_e32 v149, 31, v148
	v_ashrrev_i32_e32 v151, 31, v150
	v_cmp_lt_i32_e64 s[80:81], s10, v0
	v_ashrrev_i32_e32 v153, 31, v152
	v_ashrrev_i32_e32 v155, 31, v154
	v_cmp_gt_i32_e64 s[82:83], s12, v0
	v_cmp_gt_i32_e64 s[84:85], s14, v0
	v_cmp_gt_i32_e64 s[90:91], s16, v0
	v_add_u32_e32 v180, 23, v138
	v_add_u32_e32 v181, 0xfd0, v179
	v_add_u32_e32 v182, 46, v138
	v_cmp_gt_i32_e64 s[92:93], s18, v0
	v_add_u32_e32 v157, 11, v1
	v_add_u32_e32 v183, 0x1130, v156
	v_add_u32_e32 v184, 22, v1
	v_add_u32_e32 v185, 0x2260, v156
	v_add_u32_e32 v186, 33, v1
	v_add_u32_e32 v187, 44, v1
	v_add_u32_e32 v188, 55, v1
	s_mov_b32 s48, -1
	s_movk_i32 s33, 0x1600
	s_movk_i32 s38, 0x7fff
	s_mov_b32 s39, 0xffff0000
	s_movk_i32 s44, 0xb00
	v_mov_b32_e32 v192, 0x3ecc95a3
	v_lshlrev_b32_e32 v140, 1, v10
	v_lshlrev_b32_e32 v158, 1, v12
	v_add_u32_e32 v193, v179, v7
	v_add_u32_e32 v194, v9, v6
	v_add_u32_e32 v195, v15, v8
	v_add_u32_e32 v196, v2, v17
	v_add_u32_e32 v197, v13, v3
	v_mov_b32_e32 v198, 1
	v_mov_b32_e32 v199, 0x7f800000
	v_mov_b32_e32 v200, 0x7fc00000
	v_mov_b32_e32 v201, 0xff800000
	v_add_u32_e32 v202, v178, v16
	v_add_u32_e32 v203, v14, v18
	v_mov_b32_e32 v204, 0x580
	v_mov_b64_e32 v[98:99], v[54:55]
	v_mov_b64_e32 v[94:95], v[54:55]
	v_mov_b64_e32 v[86:87], v[54:55]
	v_mov_b64_e32 v[78:79], v[54:55]
	v_mov_b64_e32 v[74:75], v[54:55]
	v_mov_b64_e32 v[114:115], v[54:55]
	v_mov_b64_e32 v[70:71], v[54:55]
	v_mov_b64_e32 v[106:107], v[54:55]
	v_mov_b64_e32 v[62:63], v[54:55]
	v_mov_b64_e32 v[102:103], v[54:55]
	v_mov_b64_e32 v[58:59], v[54:55]
	v_mov_b64_e32 v[122:123], v[54:55]
	v_mov_b64_e32 v[90:91], v[54:55]
	v_mov_b64_e32 v[118:119], v[54:55]
	v_mov_b64_e32 v[82:83], v[54:55]
	v_mov_b64_e32 v[110:111], v[54:55]
	v_mov_b64_e32 v[66:67], v[54:55]
	v_mov_b32_e32 v9, v141
	v_mov_b32_e32 v8, v141
	v_mov_b32_e32 v7, v141
	v_mov_b32_e32 v6, v141
	s_mov_b32 s45, s78
	v_mov_b64_e32 v[12:13], v[4:5]
	v_mov_b64_e32 v[20:21], v[4:5]
	v_mov_b64_e32 v[24:25], v[4:5]
	v_mov_b64_e32 v[32:33], v[4:5]
	v_mov_b64_e32 v[2:3], v[4:5]
	v_mov_b64_e32 v[10:11], v[4:5]
	v_mov_b64_e32 v[18:19], v[4:5]
	v_mov_b64_e32 v[22:23], v[4:5]
	v_mov_b64_e32 v[30:31], v[4:5]
	v_mov_b64_e32 v[52:53], v[4:5]
	v_mov_b64_e32 v[50:51], v[4:5]
	v_mov_b64_e32 v[48:49], v[4:5]
	v_mov_b64_e32 v[46:47], v[4:5]
	v_mov_b64_e32 v[44:45], v[4:5]
	v_mov_b64_e32 v[42:43], v[4:5]
	v_mov_b32_e32 v15, v141
	v_mov_b32_e32 v17, v141
	v_mov_b32_e32 v27, v141
	v_mov_b32_e32 v29, v141
	v_mov_b32_e32 v35, v141
	v_mov_b32_e32 v37, v141
	v_mov_b32_e32 v39, v141
	v_mov_b32_e32 v41, v141
	v_mov_b32_e32 v14, v141
	v_mov_b32_e32 v16, v141
	v_mov_b32_e32 v26, v141
	v_mov_b32_e32 v28, v141
	v_mov_b32_e32 v34, v141
	v_mov_b32_e32 v36, v141
	v_mov_b32_e32 v38, v141
	v_mov_b32_e32 v40, v141
	s_branch .LBB0_936
